# nt cache-policy set plus cache_tail 16-byte paired K/V image stores
# baseline (speedup 1.0000x reference)
.LBB0_431:
	s_and_b64 vcc, exec, s[26:27]
	s_cbranch_vccz .LBB0_416
	s_load_dwordx4 s[28:31], s[20:21], 0x20
	v_and_b32_e32 v88, 1, v46
	v_cmp_ne_u32_e64 s[100:101], 0, v88
	s_lshl_b32 s26, s38, 10
	v_lshl_add_u32 v2, v46, 2, s26
	v_ashrrev_i32_e32 v3, 31, v2
	v_lshlrev_b64 v[2:3], 2, v[2:3]
	s_waitcnt lgkmcnt(0)
	v_lshl_add_u64 v[42:43], s[28:29], 0, v[2:3]
	v_lshl_add_u64 v[44:45], s[30:31], 0, v[2:3]
	global_load_dwordx4 v[26:29], v[42:43], off nt
	global_load_dwordx4 v[22:25], v[42:43], off offset:1024 nt
	global_load_dwordx4 v[30:33], v[44:45], off nt
	global_load_dwordx4 v[18:21], v[44:45], off offset:1024 nt
	global_load_dwordx4 v[10:13], v[42:43], off offset:2048 nt
	global_load_dwordx4 v[6:9], v[42:43], off offset:3072 nt
	global_load_dwordx4 v[14:17], v[44:45], off offset:2048 nt
	global_load_dwordx4 v[2:5], v[44:45], off offset:3072 nt
	v_lshl_add_u32 v44, s38, 8, v46
	v_mov_b32_e32 v39, v35
	v_mov_b32_e32 v41, v35
	v_lshl_add_u64 v[42:43], s[14:15], 0, v[38:39]
	v_lshl_add_u64 v[38:39], s[18:19], 0, v[40:41]
	v_lshlrev_b32_e32 v41, 2, v44
	v_ashrrev_i32_e32 v40, 16, v44
	v_lshrrev_b32_e32 v46, 7, v44
	v_bfe_u32 v50, v41, 6, 3
	v_bfe_u32 v51, v46, 5, 4
	v_lshl_or_b32 v50, v40, 3, v50
	v_mad_i32_i24 v50, v50, 17, v51
	v_ashrrev_i32_e32 v51, 31, v50
	v_bfe_u32 v48, v44, 7, 5
	v_lshlrev_b64 v[50:51], 12, v[50:51]
	v_mov_b32_e32 v47, v35
	v_mov_b32_e32 v49, v35
	v_lshlrev_b32_e32 v46, 4, v48
	v_lshlrev_b32_e32 v48, 6, v48
	v_lshl_add_u64 v[52:53], v[42:43], 0, v[50:51]
	v_lshl_add_u64 v[50:51], v[38:39], 0, v[50:51]
	v_lshl_add_u64 v[46:47], v[52:53], 0, v[46:47]
	v_lshl_add_u64 v[48:49], v[50:51], 0, v[48:49]
	v_bfe_u32 v45, v44, 7, 9
	v_mov_b32_e32 v37, v35
	v_lshl_add_u64 v[46:47], v[46:47], 0, v[34:35]
	v_cmp_lt_u32_e32 vcc, 31, v45
	v_lshl_add_u64 v[48:49], v[48:49], 0, v[36:37]
	s_waitcnt vmcnt(0)
	v_mov_b32_e32 v50, v26
	v_mov_b32_e32 v51, v22
	v_mov_b32_e32 v52, v30
	v_mov_b32_e32 v53, v18
	v_mov_b32_e32 v54, v10
	v_mov_b32_e32 v55, v6
	v_mov_b32_e32 v56, v14
	v_mov_b32_e32 v57, v2
	v_bfe_u32 v58, v26, 16, 1
	v_bfe_u32 v60, v28, 16, 1
	v_pk_add_f32 v[50:51], v[50:51], v[52:53]
	v_bfe_u32 v59, v27, 16, 1
	v_bfe_u32 v61, v29, 16, 1
	v_bfe_u32 v62, v30, 16, 1
	v_bfe_u32 v64, v32, 16, 1
	v_pk_add_f32 v[52:53], v[54:55], v[56:57]
	v_add3_u32 v54, v26, v58, s36
	v_add3_u32 v56, v28, v60, s36
	v_add_f32_e32 v50, 0, v50
	v_bfe_u32 v63, v31, 16, 1
	v_bfe_u32 v65, v33, 16, 1
	v_add3_u32 v55, v27, v59, s36
	v_add3_u32 v57, v29, v61, s36
	v_add3_u32 v58, v30, v62, s36
	v_add3_u32 v60, v32, v64, s36
	v_lshrrev_b32_e32 v54, 16, v54
	v_lshrrev_b32_e32 v56, 16, v56
	v_add_f32_e32 v62, v50, v51
	v_add3_u32 v59, v31, v63, s36
	v_add3_u32 v61, v33, v65, s36
	v_lshrrev_b32_e32 v58, 16, v58
	v_lshrrev_b32_e32 v60, 16, v60
	v_and_or_b32 v50, v55, s37, v54
	v_and_or_b32 v51, v57, s37, v56
	v_add_f32_e32 v52, v62, v52
	v_and_or_b32 v54, v59, s37, v58
	v_and_or_b32 v55, v61, s37, v60
	v_add_f32_e32 v52, v52, v53
	v_mov_b64_e32 v[70:71], v[50:51]
	v_mov_b64_e32 v[72:73], v[46:47]
	v_mov_b64_e32 v[74:75], v[54:55]
	v_mov_b64_e32 v[76:77], v[48:49]
	s_and_saveexec_b64 s[26:27], vcc
	s_cbranch_execz .LBB0_434
	v_lshl_or_b32 v40, v40, 9, v45
	v_subrev_u32_e32 v40, 32, v40
	v_and_b32_e32 v46, 0x1fc, v41
	v_ashrrev_i32_e32 v41, 31, v40
	v_lshlrev_b64 v[40:41], 11, v[40:41]
	v_lshl_or_b32 v40, v46, 2, v40
	v_lshl_add_u64 v[46:47], s[24:25], 0, v[40:41]
	global_store_dwordx4 v[46:47], v[26:29], off sc0 sc1 nt
	s_nop 1
	v_lshl_add_u64 v[26:27], s[16:17], 0, v[40:41]
	global_store_dwordx4 v[26:27], v[30:33], off sc0 sc1 nt
	s_nop 1
.LBB0_434:
	s_or_b64 exec, exec, s[26:27]
	v_add_u32_e32 v29, 64, v44
	v_lshlrev_b32_e32 v27, 2, v29
	v_ashrrev_i32_e32 v26, 16, v29
	v_lshrrev_b32_e32 v30, 7, v29
	v_bfe_u32 v31, v27, 6, 3
	v_lshl_or_b32 v31, v26, 3, v31
	v_bfe_u32 v30, v30, 5, 4
	v_mad_i32_i24 v30, v31, 17, v30
	v_ashrrev_i32_e32 v31, 31, v30
	v_bfe_u32 v28, v29, 7, 9
	v_lshlrev_b64 v[30:31], 12, v[30:31]
	v_bfe_u32 v29, v29, 7, 5
	v_lshl_add_u64 v[32:33], v[42:43], 0, v[30:31]
	v_lshlrev_b32_e32 v40, 4, v29
	v_mov_b32_e32 v41, v35
	v_lshl_add_u64 v[32:33], v[32:33], 0, v[40:41]
	v_bfe_u32 v40, v22, 16, 1
	v_add3_u32 v40, v22, v40, s36
	v_bfe_u32 v41, v23, 16, 1
	v_lshrrev_b32_e32 v40, 16, v40
	v_add3_u32 v41, v23, v41, s36
	v_and_or_b32 v40, v41, s37, v40
	v_bfe_u32 v41, v24, 16, 1
	v_add3_u32 v41, v24, v41, s36
	v_bfe_u32 v45, v25, 16, 1
	v_lshrrev_b32_e32 v41, 16, v41
	v_add3_u32 v45, v25, v45, s36
	v_lshl_add_u64 v[32:33], v[32:33], 0, v[34:35]
	v_and_or_b32 v41, v45, s37, v41
	v_cndmask_b32_e64 v78, v40, v70, s[100:101]
	v_cndmask_b32_e64 v79, v41, v71, s[100:101]
	v_subrev_u32_e32 v86, 8, v32
	s_nop 0
	v_mov_b32_dpp v80, v78 quad_perm:[1,0,3,2] row_mask:0xf bank_mask:0xf
	v_mov_b32_dpp v81, v79 quad_perm:[1,0,3,2] row_mask:0xf bank_mask:0xf
	v_cndmask_b32_e64 v86, v72, v86, s[100:101]
	v_cndmask_b32_e64 v87, v73, v33, s[100:101]
	v_cndmask_b32_e64 v82, v70, v80, s[100:101]
	v_cndmask_b32_e64 v83, v71, v81, s[100:101]
	v_cndmask_b32_e64 v84, v80, v40, s[100:101]
	v_cndmask_b32_e64 v85, v81, v41, s[100:101]
	global_store_dwordx4 v[86:87], v[82:85], off sc0 sc1
	s_nop 1
	v_lshl_add_u64 v[30:31], v[38:39], 0, v[30:31]
	v_lshlrev_b32_e32 v32, 6, v29
	v_mov_b32_e32 v33, v35
	v_bfe_u32 v29, v18, 16, 1
	v_lshl_add_u64 v[30:31], v[30:31], 0, v[32:33]
	v_add3_u32 v29, v18, v29, s36
	v_bfe_u32 v32, v19, 16, 1
	v_lshrrev_b32_e32 v29, 16, v29
	v_add3_u32 v32, v19, v32, s36
	v_and_or_b32 v32, v32, s37, v29
	v_bfe_u32 v29, v20, 16, 1
	v_add3_u32 v29, v20, v29, s36
	v_bfe_u32 v33, v21, 16, 1
	v_lshrrev_b32_e32 v29, 16, v29
	v_add3_u32 v33, v21, v33, s36
	v_lshl_add_u64 v[30:31], v[30:31], 0, v[36:37]
	v_and_or_b32 v33, v33, s37, v29
	v_cmp_lt_u32_e32 vcc, 31, v28
	v_cndmask_b32_e64 v78, v32, v74, s[100:101]
	v_cndmask_b32_e64 v79, v33, v75, s[100:101]
	v_subrev_u32_e32 v86, 8, v30
	s_nop 0
	v_mov_b32_dpp v80, v78 quad_perm:[1,0,3,2] row_mask:0xf bank_mask:0xf
	v_mov_b32_dpp v81, v79 quad_perm:[1,0,3,2] row_mask:0xf bank_mask:0xf
	v_cndmask_b32_e64 v86, v76, v86, s[100:101]
	v_cndmask_b32_e64 v87, v77, v31, s[100:101]
	v_cndmask_b32_e64 v82, v74, v80, s[100:101]
	v_cndmask_b32_e64 v83, v75, v81, s[100:101]
	v_cndmask_b32_e64 v84, v80, v32, s[100:101]
	v_cndmask_b32_e64 v85, v81, v33, s[100:101]
	global_store_dwordx4 v[86:87], v[82:85], off sc0 sc1
	s_nop 1
	s_and_saveexec_b64 s[26:27], vcc
	s_cbranch_execz .LBB0_436
	v_lshl_or_b32 v26, v26, 9, v28
	v_subrev_u32_e32 v26, 32, v26
	v_and_b32_e32 v29, 0x1fc, v27
	v_ashrrev_i32_e32 v27, 31, v26
	v_lshlrev_b64 v[26:27], 11, v[26:27]
	v_lshl_or_b32 v26, v29, 2, v26
	v_lshl_add_u64 v[28:29], s[24:25], 0, v[26:27]
	global_store_dwordx4 v[28:29], v[22:25], off sc0 sc1 nt
	s_nop 1
	v_lshl_add_u64 v[22:23], s[16:17], 0, v[26:27]
	global_store_dwordx4 v[22:23], v[18:21], off sc0 sc1 nt
	s_nop 1
.LBB0_436:
	s_or_b64 exec, exec, s[26:27]
	v_add_u32_e32 v21, 0x80, v44
	v_lshlrev_b32_e32 v19, 2, v21
	v_ashrrev_i32_e32 v18, 16, v21
	v_lshrrev_b32_e32 v22, 7, v21
	v_bfe_u32 v23, v19, 6, 3
	v_lshl_or_b32 v23, v18, 3, v23
	v_bfe_u32 v22, v22, 5, 4
	v_mad_i32_i24 v22, v23, 17, v22
	v_ashrrev_i32_e32 v23, 31, v22
	v_bfe_u32 v20, v21, 7, 9
	v_lshlrev_b64 v[22:23], 12, v[22:23]
	v_bfe_u32 v21, v21, 7, 5
	v_lshl_add_u64 v[24:25], v[42:43], 0, v[22:23]
	v_lshlrev_b32_e32 v26, 4, v21
	v_mov_b32_e32 v27, v35
	v_lshl_add_u64 v[24:25], v[24:25], 0, v[26:27]
	v_bfe_u32 v26, v10, 16, 1
	v_add3_u32 v26, v10, v26, s36
	v_bfe_u32 v27, v11, 16, 1
	v_lshrrev_b32_e32 v26, 16, v26
	v_add3_u32 v27, v11, v27, s36
	v_and_or_b32 v26, v27, s37, v26
	v_bfe_u32 v27, v12, 16, 1
	v_add3_u32 v27, v12, v27, s36
	v_bfe_u32 v28, v13, 16, 1
	v_lshrrev_b32_e32 v27, 16, v27
	v_add3_u32 v28, v13, v28, s36
	v_lshl_add_u64 v[24:25], v[24:25], 0, v[34:35]
	v_and_or_b32 v27, v28, s37, v27
	v_mov_b64_e32 v[70:71], v[26:27]
	v_mov_b64_e32 v[72:73], v[24:25]
	v_lshl_add_u64 v[22:23], v[38:39], 0, v[22:23]
	v_lshlrev_b32_e32 v24, 6, v21
	v_mov_b32_e32 v25, v35
	v_bfe_u32 v21, v14, 16, 1
	v_lshl_add_u64 v[22:23], v[22:23], 0, v[24:25]
	v_add3_u32 v21, v14, v21, s36
	v_bfe_u32 v24, v15, 16, 1
	v_lshrrev_b32_e32 v21, 16, v21
	v_add3_u32 v24, v15, v24, s36
	v_and_or_b32 v24, v24, s37, v21
	v_bfe_u32 v21, v16, 16, 1
	v_add3_u32 v21, v16, v21, s36
	v_bfe_u32 v25, v17, 16, 1
	v_lshrrev_b32_e32 v21, 16, v21
	v_add3_u32 v25, v17, v25, s36
	v_lshl_add_u64 v[22:23], v[22:23], 0, v[36:37]
	v_and_or_b32 v25, v25, s37, v21
	v_cmp_lt_u32_e32 vcc, 31, v20
	v_mov_b64_e32 v[74:75], v[24:25]
	v_mov_b64_e32 v[76:77], v[22:23]
	s_and_saveexec_b64 s[26:27], vcc
	s_cbranch_execz .LBB0_438
	v_lshl_or_b32 v18, v18, 9, v20
	v_subrev_u32_e32 v18, 32, v18
	v_and_b32_e32 v21, 0x1fc, v19
	v_ashrrev_i32_e32 v19, 31, v18
	v_lshlrev_b64 v[18:19], 11, v[18:19]
	v_lshl_or_b32 v18, v21, 2, v18
	v_lshl_add_u64 v[20:21], s[24:25], 0, v[18:19]
	global_store_dwordx4 v[20:21], v[10:13], off sc0 sc1 nt
	s_nop 1
	v_lshl_add_u64 v[10:11], s[16:17], 0, v[18:19]
	global_store_dwordx4 v[10:11], v[14:17], off sc0 sc1 nt
	s_nop 1
.LBB0_438:
	s_or_b64 exec, exec, s[26:27]
	v_add_u32_e32 v13, 0xc0, v44
	v_lshlrev_b32_e32 v11, 2, v13
	v_ashrrev_i32_e32 v10, 16, v13
	v_lshrrev_b32_e32 v14, 7, v13
	v_bfe_u32 v15, v11, 6, 3
	v_lshl_or_b32 v15, v10, 3, v15
	v_bfe_u32 v14, v14, 5, 4
	v_mad_i32_i24 v14, v15, 17, v14
	v_ashrrev_i32_e32 v15, 31, v14
	v_bfe_u32 v12, v13, 7, 9
	v_lshlrev_b64 v[14:15], 12, v[14:15]
	v_bfe_u32 v13, v13, 7, 5
	v_lshl_add_u64 v[16:17], v[42:43], 0, v[14:15]
	v_lshlrev_b32_e32 v18, 4, v13
	v_mov_b32_e32 v19, v35
	v_lshl_add_u64 v[16:17], v[16:17], 0, v[18:19]
	v_bfe_u32 v18, v6, 16, 1
	v_add3_u32 v18, v6, v18, s36
	v_bfe_u32 v19, v7, 16, 1
	v_lshrrev_b32_e32 v18, 16, v18
	v_add3_u32 v19, v7, v19, s36
	v_and_or_b32 v18, v19, s37, v18
	v_bfe_u32 v19, v8, 16, 1
	v_add3_u32 v19, v8, v19, s36
	v_bfe_u32 v20, v9, 16, 1
	v_lshrrev_b32_e32 v19, 16, v19
	v_add3_u32 v20, v9, v20, s36
	v_lshl_add_u64 v[16:17], v[16:17], 0, v[34:35]
	v_and_or_b32 v19, v20, s37, v19
	v_lshlrev_b32_e32 v34, 6, v13
	v_bfe_u32 v13, v2, 16, 1
	v_cndmask_b32_e64 v78, v18, v70, s[100:101]
	v_cndmask_b32_e64 v79, v19, v71, s[100:101]
	v_subrev_u32_e32 v86, 8, v16
	s_nop 0
	v_mov_b32_dpp v80, v78 quad_perm:[1,0,3,2] row_mask:0xf bank_mask:0xf
	v_mov_b32_dpp v81, v79 quad_perm:[1,0,3,2] row_mask:0xf bank_mask:0xf
	v_cndmask_b32_e64 v86, v72, v86, s[100:101]
	v_cndmask_b32_e64 v87, v73, v17, s[100:101]
	v_cndmask_b32_e64 v82, v70, v80, s[100:101]
	v_cndmask_b32_e64 v83, v71, v81, s[100:101]
	v_cndmask_b32_e64 v84, v80, v18, s[100:101]
	v_cndmask_b32_e64 v85, v81, v19, s[100:101]
	global_store_dwordx4 v[86:87], v[82:85], off sc0 sc1
	s_nop 1
	v_add3_u32 v13, v2, v13, s36
	v_bfe_u32 v16, v3, 16, 1
	v_lshrrev_b32_e32 v13, 16, v13
	v_add3_u32 v16, v3, v16, s36
	v_and_or_b32 v16, v16, s37, v13
	v_bfe_u32 v13, v4, 16, 1
	v_lshl_add_u64 v[14:15], v[38:39], 0, v[14:15]
	v_add3_u32 v13, v4, v13, s36
	v_bfe_u32 v17, v5, 16, 1
	v_lshl_add_u64 v[14:15], v[14:15], 0, v[34:35]
	v_lshrrev_b32_e32 v13, 16, v13
	v_add3_u32 v17, v5, v17, s36
	v_lshl_add_u64 v[14:15], v[14:15], 0, v[36:37]
	v_and_or_b32 v17, v17, s37, v13
	v_cmp_lt_u32_e32 vcc, 31, v12
	v_cndmask_b32_e64 v78, v16, v74, s[100:101]
	v_cndmask_b32_e64 v79, v17, v75, s[100:101]
	v_subrev_u32_e32 v86, 8, v14
	s_nop 0
	v_mov_b32_dpp v80, v78 quad_perm:[1,0,3,2] row_mask:0xf bank_mask:0xf
	v_mov_b32_dpp v81, v79 quad_perm:[1,0,3,2] row_mask:0xf bank_mask:0xf
	v_cndmask_b32_e64 v86, v76, v86, s[100:101]
	v_cndmask_b32_e64 v87, v77, v15, s[100:101]
	v_cndmask_b32_e64 v82, v74, v80, s[100:101]
	v_cndmask_b32_e64 v83, v75, v81, s[100:101]
	v_cndmask_b32_e64 v84, v80, v16, s[100:101]
	v_cndmask_b32_e64 v85, v81, v17, s[100:101]
	global_store_dwordx4 v[86:87], v[82:85], off sc0 sc1
	s_nop 1
	s_and_saveexec_b64 s[26:27], vcc
	s_cbranch_execz .LBB0_415
	v_lshl_or_b32 v10, v10, 9, v12
	v_subrev_u32_e32 v10, 32, v10
	v_and_b32_e32 v13, 0x1fc, v11
	v_ashrrev_i32_e32 v11, 31, v10
	v_lshlrev_b64 v[10:11], 11, v[10:11]
	v_lshl_or_b32 v10, v13, 2, v10
	v_lshl_add_u64 v[12:13], s[24:25], 0, v[10:11]
	global_store_dwordx4 v[12:13], v[6:9], off sc0 sc1 nt
	s_nop 1
	v_lshl_add_u64 v[6:7], s[16:17], 0, v[10:11]
	global_store_dwordx4 v[6:7], v[2:5], off sc0 sc1 nt
	s_nop 1
	s_branch .LBB0_415
